# rowpass: modulation vectors staged in LDS + next-row loads issued before this row's stores (on v9)
# speedup vs baseline: 1.0079x; 1.0079x over previous
; DI void rowpass(const Params& p, int l, bool first, int wv, char* smem) {
;     ...
;   float* lg_post = (float*)smem;
;   float* lg_pre = (float*)smem + 2048;
;   {
;     const int t4 = (wv * 64 + lane_) * 4;
;     if (!first) *(f32x4*)(lg_post + t4) = *(const f32x4*)(p.post_g + l * DM + t4);
;     if (first || l < 3) *(f32x4*)(lg_pre + t4) = *(const f32x4*)(p.pre_g + lnext * DM + t4);
;     __syncthreads();
;   }
;   for (int R = blockIdx.x * 8 + w; R < NTOK; R += gridDim.x * 8) {
.LBB0_101:
	v_readlane_b32 s0, v253, 55
	s_add_i32 s6, s1, s0
	s_cmpk_gt_i32 s6, 0x23ff
	s_waitcnt lgkmcnt(0)
	s_barrier
	s_cbranch_scc1 .LBB0_117
	v_ashrrev_i32_e32 v131, 31, v130
	v_readlane_b32 s36, v253, 21
	v_lshlrev_b64 v[2:3], 1, v[130:131]
	v_readlane_b32 s40, v253, 25
	v_readlane_b32 s41, v253, 26
	v_readlane_b32 s42, v253, 27
	v_readlane_b32 s43, v253, 28
	v_readlane_b32 s44, v253, 29
	v_readlane_b32 s45, v253, 30
	v_readlane_b32 s46, v253, 31
	v_readlane_b32 s47, v253, 32
	v_readlane_b32 s48, v253, 33
	v_readlane_b32 s49, v253, 34
	v_readlane_b32 s50, v253, 35
	v_readlane_b32 s51, v253, 36
	s_cmp_lt_u32 s81, 4
	v_lshl_add_u64 v[134:135], s[48:49], 0, v[2:3]
	v_readlane_b32 s40, v254, 22
	s_cselect_b64 s[8:9], -1, 0
	v_lshlrev_b32_e32 v212, 2, v130
	v_lshl_add_u64 v[132:133], s[94:95], 0, v[2:3]
	v_readlane_b32 s41, v254, 23
	v_readlane_b32 s42, v254, 24
	v_readlane_b32 s43, v254, 25
	v_readlane_b32 s44, v254, 26
	v_readlane_b32 s45, v254, 27
	v_readlane_b32 s46, v254, 28
	v_readlane_b32 s47, v254, 29
	v_readlane_b32 s48, v254, 30
	v_readlane_b32 s49, v254, 31
	v_readlane_b32 s50, v254, 32
	v_readlane_b32 s51, v254, 33
	v_readlane_b32 s52, v254, 34
	v_readlane_b32 s53, v254, 35
	v_readlane_b32 s54, v254, 36
	v_readlane_b32 s55, v254, 37
	v_lshl_add_u64 v[136:137], s[96:97], 0, v[2:3]
	v_readlane_b32 s37, v253, 22
	v_readlane_b32 s38, v253, 23
	v_readlane_b32 s39, v253, 24
	s_mov_b32 s0, 0
	v_writelane_b32 v255, s0, 62
	s_branch .LBB0_104

; DI float bf_lo(unsigned u) { return __uint_as_float(u << 16); }
; DI float bf_hi(unsigned u) { return __uint_as_float(u & 0xffff0000u); }
; DI void rowpass(const Params& p, int l, bool first, int wv, char* smem) {
;     ...
;     const float* hin; float* hout;
;     if (isctx) {
;       hout = p.hc + (size_t)(b * 256 + j) * DM;
;       hin = (first || l == 0) ? p.ctx + (size_t)(b * 256 + j) * DM : hout;
;     } else {
;       hout = p.out + (size_t)(b * 2048 + (j - 256)) * DM;
;       hin = (first || l == 0) ? p.x + (size_t)(b * 2048 + (j - 256)) * DM : hout;
;     }
;     f32x4 hv[8];
; #pragma unroll
;     for (int i = 0; i < 8; ++i) hv[i] = *(const f32x4*)(hin + i * 256 + lane * 4);
;     if (!first) {
;       f32x4 yv[8];
;       float ss = 0.f;
;       if (!isctx) {
;         const u16* yp = p.y + (size_t)R * DM;
; #pragma unroll
;         for (int i = 0; i < 8; ++i) {
;           const u32x2 u = *(const u32x2*)(yp + i * 256 + lane * 4);
;           yv[i][0] = bf_lo(u[0]); yv[i][1] = bf_hi(u[0]); yv[i][2] = bf_lo(u[1]); yv[i][3] = bf_hi(u[1]);
;         }
.LBB0_109:
	s_ashr_i32 s21, s20, 31
	s_lshl_b64 s[20:21], s[20:21], 13
	s_add_u32 s0, s0, s20
	s_addc_u32 s1, s1, s21
	s_add_u32 s7, s10, s20
	s_addc_u32 s20, s11, s21
	s_and_b64 s[10:11], s[8:9], exec
	s_cselect_b32 s10, s20, s1
	s_cselect_b32 s7, s7, s0
	v_readlane_b32 s21, v255, 62
	s_cmp_lg_u32 s21, 0
	s_cbranch_scc1 .Lrp_use_pf
	v_mov_b32_e32 v66, s7
	v_mov_b32_e32 v67, s10
	v_lshl_add_u64 v[66:67], v[130:131], 2, v[66:67]
	global_load_dwordx4 v[94:97], v[66:67], off
	global_load_dwordx4 v[90:93], v[66:67], off offset:1024
	global_load_dwordx4 v[86:89], v[66:67], off offset:2048
	global_load_dwordx4 v[82:85], v[66:67], off offset:3072
	v_add_co_u32_e32 v66, vcc, 0x1000, v66
	s_mov_b64 s[10:11], -1
	s_nop 0
	v_addc_co_u32_e32 v67, vcc, 0, v67, vcc
	global_load_dwordx4 v[78:81], v[66:67], off
	global_load_dwordx4 v[74:77], v[66:67], off offset:1024
	global_load_dwordx4 v[70:73], v[66:67], off offset:2048
	s_nop 0
	global_load_dwordx4 v[66:69], v[66:67], off offset:3072
	s_and_b64 vcc, exec, s[12:13]
	s_cbranch_vccz .LBB0_111
	s_ashr_i32 s7, s6, 31
	s_lshl_b64 s[10:11], s[6:7], 12
	v_lshl_add_u64 v[98:99], v[132:133], 0, s[10:11]
	global_load_dwordx2 v[100:101], v[98:99], off
	global_load_dwordx2 v[102:103], v[98:99], off offset:512
	global_load_dwordx2 v[104:105], v[98:99], off offset:1024
	global_load_dwordx2 v[106:107], v[98:99], off offset:1536
	global_load_dwordx2 v[108:109], v[98:99], off offset:2048
	global_load_dwordx2 v[110:111], v[98:99], off offset:2560
	global_load_dwordx2 v[112:113], v[98:99], off offset:3072
	s_nop 0
	global_load_dwordx2 v[98:99], v[98:99], off offset:3584
	s_mov_b64 s[10:11], 0
	s_waitcnt vmcnt(7)
	v_lshlrev_b32_e32 v138, 16, v100
	v_and_b32_e32 v139, 0xffff0000, v100
	v_lshlrev_b32_e32 v140, 16, v101
	v_and_b32_e32 v141, 0xffff0000, v101
	s_waitcnt vmcnt(6)
	v_lshlrev_b32_e32 v142, 16, v102
	v_and_b32_e32 v143, 0xffff0000, v102
	v_lshlrev_b32_e32 v144, 16, v103
	v_and_b32_e32 v145, 0xffff0000, v103
	s_waitcnt vmcnt(5)
	v_lshlrev_b32_e32 v146, 16, v104
	v_and_b32_e32 v147, 0xffff0000, v104
	v_lshlrev_b32_e32 v148, 16, v105
	v_and_b32_e32 v149, 0xffff0000, v105
	s_waitcnt vmcnt(4)
	v_lshlrev_b32_e32 v150, 16, v106
	v_and_b32_e32 v151, 0xffff0000, v106
	v_lshlrev_b32_e32 v152, 16, v107
	v_and_b32_e32 v153, 0xffff0000, v107
	s_waitcnt vmcnt(3)
	v_lshlrev_b32_e32 v166, 16, v108
	v_and_b32_e32 v167, 0xffff0000, v108
	v_lshlrev_b32_e32 v168, 16, v109
	v_and_b32_e32 v169, 0xffff0000, v109
	s_waitcnt vmcnt(2)
	v_lshlrev_b32_e32 v170, 16, v110
	v_and_b32_e32 v171, 0xffff0000, v110
	v_lshlrev_b32_e32 v154, 16, v111
	v_and_b32_e32 v155, 0xffff0000, v111
	s_waitcnt vmcnt(1)
	v_lshlrev_b32_e32 v156, 16, v112
	v_and_b32_e32 v157, 0xffff0000, v112
	v_lshlrev_b32_e32 v158, 16, v113
	v_and_b32_e32 v159, 0xffff0000, v113
	s_waitcnt vmcnt(0)
	v_lshlrev_b32_e32 v160, 16, v98
	v_and_b32_e32 v161, 0xffff0000, v98
	v_lshlrev_b32_e32 v162, 16, v99
	v_and_b32_e32 v163, 0xffff0000, v99
	s_branch .LBB0_111
.Lrp_use_pf:
	s_and_b64 vcc, exec, s[4:5]
	s_cbranch_vccnz .Lrp_w8
	s_waitcnt vmcnt(16)
	s_branch .Lrp_mv
.Lrp_w8:
	s_waitcnt vmcnt(8)
.Lrp_mv:
	v_mov_b64_e32 v[94:95], v[180:181]
	v_mov_b64_e32 v[96:97], v[182:183]
	v_mov_b64_e32 v[90:91], v[184:185]
	v_mov_b64_e32 v[92:93], v[186:187]
	v_mov_b64_e32 v[86:87], v[188:189]
	v_mov_b64_e32 v[88:89], v[190:191]
	v_mov_b64_e32 v[82:83], v[192:193]
	v_mov_b64_e32 v[84:85], v[194:195]
	v_mov_b64_e32 v[78:79], v[196:197]
	v_mov_b64_e32 v[80:81], v[198:199]
	v_mov_b64_e32 v[74:75], v[200:201]
	v_mov_b64_e32 v[76:77], v[202:203]
	v_mov_b64_e32 v[70:71], v[204:205]
	v_mov_b64_e32 v[72:73], v[206:207]
	v_mov_b64_e32 v[66:67], v[208:209]
	v_mov_b64_e32 v[68:69], v[210:211]
	v_lshlrev_b32_e32 v138, 16, v214
	v_and_b32_e32 v139, 0xffff0000, v214
	v_lshlrev_b32_e32 v140, 16, v215
	v_and_b32_e32 v141, 0xffff0000, v215
	v_lshlrev_b32_e32 v142, 16, v216
	v_and_b32_e32 v143, 0xffff0000, v216
	v_lshlrev_b32_e32 v144, 16, v217
	v_and_b32_e32 v145, 0xffff0000, v217
	v_lshlrev_b32_e32 v146, 16, v218
	v_and_b32_e32 v147, 0xffff0000, v218
	v_lshlrev_b32_e32 v148, 16, v219
	v_and_b32_e32 v149, 0xffff0000, v219
	v_lshlrev_b32_e32 v150, 16, v220
	v_and_b32_e32 v151, 0xffff0000, v220
	v_lshlrev_b32_e32 v152, 16, v221
	v_and_b32_e32 v153, 0xffff0000, v221
	v_lshlrev_b32_e32 v166, 16, v222
	v_and_b32_e32 v167, 0xffff0000, v222
	v_lshlrev_b32_e32 v168, 16, v223
	v_and_b32_e32 v169, 0xffff0000, v223
	v_lshlrev_b32_e32 v170, 16, v224
	v_and_b32_e32 v171, 0xffff0000, v224
	v_lshlrev_b32_e32 v154, 16, v225
	v_and_b32_e32 v155, 0xffff0000, v225
	v_lshlrev_b32_e32 v156, 16, v226
	v_and_b32_e32 v157, 0xffff0000, v226
	v_lshlrev_b32_e32 v158, 16, v227
	v_and_b32_e32 v159, 0xffff0000, v227
	v_lshlrev_b32_e32 v160, 16, v228
	v_and_b32_e32 v161, 0xffff0000, v228
	v_lshlrev_b32_e32 v162, 16, v229
	v_and_b32_e32 v163, 0xffff0000, v229
	s_mov_b64 s[10:11], 0

; DI float bf_lo(unsigned u) { return __uint_as_float(u << 16); }
; DI float bf_hi(unsigned u) { return __uint_as_float(u & 0xffff0000u); }
; DI void rowpass(const Params& p, int l, bool first, int wv, char* smem) {
;     ...
;   for (int R = blockIdx.x * 8 + w; R < NTOK; R += gridDim.x * 8) {
;     const int b = R / TPB, j = R - b * TPB;
;     const bool isctx = j < 256;
;     const int mr = isctx ? 4 : b;
;     if (!first && l == 3 && isctx) continue;
;     const float* hin; float* hout;
;     if (isctx) {
;       hout = p.hc + (size_t)(b * 256 + j) * DM;
;       hin = (first || l == 0) ? p.ctx + (size_t)(b * 256 + j) * DM : hout;
;     } else {
;       hout = p.out + (size_t)(b * 2048 + (j - 256)) * DM;
;       hin = (first || l == 0) ? p.x + (size_t)(b * 2048 + (j - 256)) * DM : hout;
;     }
;     f32x4 hv[8];
; #pragma unroll
;     for (int i = 0; i < 8; ++i) hv[i] = *(const f32x4*)(hin + i * 256 + lane * 4);
;     ...
;       if (!isctx) {
;         const u16* yp = p.y + (size_t)R * DM;
; #pragma unroll
;         for (int i = 0; i < 8; ++i) {
;           const u32x2 u = *(const u32x2*)(yp + i * 256 + lane * 4);
;           yv[i][0] = bf_lo(u[0]); yv[i][1] = bf_hi(u[0]); yv[i][2] = bf_lo(u[1]); yv[i][3] = bf_hi(u[1]);
.LBB0_115:
	v_readlane_b32 s2, v253, 56
	s_add_i32 s2, s6, s2
	s_cmpk_gt_i32 s2, 0x23ff
	s_cbranch_scc1 .Lrp_nopf
	s_mul_hi_i32 s3, s2, 0x38e38e39
	s_lshr_b32 s7, s3, 31
	s_ashr_i32 s3, s3, 9
	s_add_i32 s3, s3, s7
	s_mul_i32 s7, s3, 0xfffff700
	s_add_i32 s7, s7, s2
	s_cmpk_lt_i32 s7, 0x100
	s_cbranch_scc1 .Lrp_nopf
	s_lshl_b32 s3, s3, 8
	s_sub_i32 s3, s2, s3
	s_add_i32 s10, s3, 0xffffff00
	s_ashr_i32 s11, s10, 31
	s_lshl_b64 s[10:11], s[10:11], 13
	v_readlane_b32 s12, v254, 22
	v_readlane_b32 s13, v254, 23
	v_readlane_b32 s24, v253, 27
	v_readlane_b32 s21, v253, 28
	s_and_b64 vcc, s[8:9], exec
	s_cselect_b32 s12, s12, s24
	s_cselect_b32 s13, s13, s21
	s_add_u32 s12, s12, s10
	s_addc_u32 s13, s13, s11
	v_mov_b32_e32 v238, s12
	v_mov_b32_e32 v239, s13
	v_lshl_add_u64 v[238:239], v[130:131], 2, v[238:239]
	global_load_dwordx4 v[180:183], v[238:239], off
	global_load_dwordx4 v[184:187], v[238:239], off offset:1024
	global_load_dwordx4 v[188:191], v[238:239], off offset:2048
	global_load_dwordx4 v[192:195], v[238:239], off offset:3072
	s_mov_b64 s[10:11], 0x1000
	v_lshl_add_u64 v[238:239], v[238:239], 0, s[10:11]
	global_load_dwordx4 v[196:199], v[238:239], off
	global_load_dwordx4 v[200:203], v[238:239], off offset:1024
	global_load_dwordx4 v[204:207], v[238:239], off offset:2048
	global_load_dwordx4 v[208:211], v[238:239], off offset:3072
	s_ashr_i32 s3, s2, 31
	s_lshl_b64 s[10:11], s[2:3], 12
	v_lshl_add_u64 v[240:241], v[132:133], 0, s[10:11]
	global_load_dwordx2 v[214:215], v[240:241], off
	global_load_dwordx2 v[216:217], v[240:241], off offset:512
	global_load_dwordx2 v[218:219], v[240:241], off offset:1024
	global_load_dwordx2 v[220:221], v[240:241], off offset:1536
	global_load_dwordx2 v[222:223], v[240:241], off offset:2048
	global_load_dwordx2 v[224:225], v[240:241], off offset:2560
	global_load_dwordx2 v[226:227], v[240:241], off offset:3072
	global_load_dwordx2 v[228:229], v[240:241], off offset:3584
	s_mov_b32 s2, 1
	s_branch .Lrp_pfset
.Lrp_nopf:
	s_mov_b32 s2, 0
.Lrp_pfset:
	v_writelane_b32 v255, s2, 62
	v_mul_f32_e32 v0, v139, v139
	v_mul_f32_e32 v164, v143, v143
	v_fmac_f32_e32 v164, v142, v142
	v_mul_f32_e32 v165, v147, v147
	v_fmac_f32_e32 v0, v138, v138
	v_fmac_f32_e32 v164, v144, v144
	v_fmac_f32_e32 v165, v146, v146
	v_mul_f32_e32 v172, v151, v151
	v_fmac_f32_e32 v0, v140, v140
	v_fmac_f32_e32 v164, v145, v145
	v_fmac_f32_e32 v165, v148, v148
	v_fmac_f32_e32 v172, v150, v150
	v_mul_f32_e32 v173, v167, v167
	v_fmac_f32_e32 v0, v141, v141
	v_fmac_f32_e32 v165, v149, v149
	v_fmac_f32_e32 v172, v152, v152
	v_fmac_f32_e32 v173, v166, v166
	v_mul_f32_e32 v174, v171, v171
	v_add_f32_e32 v0, v0, v164
	v_fmac_f32_e32 v172, v153, v153
	v_fmac_f32_e32 v173, v168, v168
	v_fmac_f32_e32 v174, v170, v170
	v_mul_f32_e32 v175, v157, v157
	v_add_f32_e32 v0, v165, v0
	v_fmac_f32_e32 v173, v169, v169
	v_fmac_f32_e32 v174, v154, v154
	v_fmac_f32_e32 v175, v156, v156
	v_mul_f32_e32 v176, v161, v161
	v_add_f32_e32 v0, v172, v0
	v_fmac_f32_e32 v174, v155, v155
	v_fmac_f32_e32 v175, v158, v158
	v_fmac_f32_e32 v176, v160, v160
	v_add_f32_e32 v0, v173, v0
	v_fmac_f32_e32 v175, v159, v159
	v_fmac_f32_e32 v176, v162, v162
	v_add_f32_e32 v0, v174, v0
	v_fmac_f32_e32 v176, v163, v163
	v_add_f32_e32 v0, v175, v0
	v_add_f32_e32 v0, v176, v0
	v_mov_b32_e32 v164, v0
	s_nop 1
	v_permlane32_swap_b32_e32 v0, v164
	v_add_f32_e32 v0, v0, v164
	ds_swizzle_b32 v164, v0 offset:swizzle(SWAP,16)
	s_mov_b32 s2, 0x800000
	ds_read_b128 v[172:175], v212
	s_waitcnt lgkmcnt(1)
	v_add_f32_e32 v0, v0, v164
	ds_swizzle_b32 v164, v0 offset:swizzle(SWAP,8)
	s_waitcnt lgkmcnt(0)
	v_add_f32_e32 v0, v0, v164
	ds_swizzle_b32 v164, v0 offset:swizzle(SWAP,4)
	s_waitcnt lgkmcnt(0)
	v_add_f32_e32 v0, v0, v164
	ds_swizzle_b32 v164, v0 offset:swizzle(SWAP,2)
	s_waitcnt lgkmcnt(0)
	v_add_f32_e32 v0, v0, v164
	ds_swizzle_b32 v164, v0 offset:swizzle(SWAP,1)
	s_waitcnt lgkmcnt(0)
	v_add_f32_e32 v0, v0, v164
	v_fmamk_f32 v0, v0, 0x3a000000, v232
	v_cmp_gt_f32_e32 vcc, s2, v0
	v_mul_f32_e32 v164, 0x4b800000, v0
	s_nop 0
	v_cndmask_b32_e32 v0, v0, v164, vcc
	v_rsq_f32_e32 v0, v0
	s_nop 0
	v_mul_f32_e32 v164, 0x45800000, v0
	v_cndmask_b32_e32 v0, v0, v164, vcc
	v_pk_mul_f32 v[138:139], v[138:139], v[0:1] op_sel_hi:[1,0]
	v_lshl_add_u64 v[164:165], v[130:131], 2, s[0:1]
	v_pk_mul_f32 v[138:139], v[172:173], v[138:139]
	s_movk_i32 s0, 0x1000
	v_pk_fma_f32 v[94:95], v[126:127], v[138:139], v[94:95]
	v_pk_mul_f32 v[126:127], v[140:141], v[0:1] op_sel_hi:[1,0]
	v_pk_mul_f32 v[138:139], v[142:143], v[0:1] op_sel_hi:[1,0]
	v_pk_mul_f32 v[126:127], v[174:175], v[126:127]
	s_nop 0
	v_pk_fma_f32 v[96:97], v[128:129], v[126:127], v[96:97]
	ds_read_b128 v[126:129], v212 offset:1024
	global_store_dwordx4 v[164:165], v[94:97], off
	s_waitcnt lgkmcnt(0)
	v_pk_mul_f32 v[126:127], v[126:127], v[138:139]
	s_nop 0
	v_pk_fma_f32 v[90:91], v[122:123], v[126:127], v[90:91]
	v_pk_mul_f32 v[122:123], v[144:145], v[0:1] op_sel_hi:[1,0]
	v_pk_mul_f32 v[126:127], v[146:147], v[0:1] op_sel_hi:[1,0]
	v_pk_mul_f32 v[122:123], v[128:129], v[122:123]
	s_nop 0
	v_pk_fma_f32 v[92:93], v[124:125], v[122:123], v[92:93]
	ds_read_b128 v[122:125], v212 offset:2048
	global_store_dwordx4 v[164:165], v[90:93], off offset:1024
	s_waitcnt lgkmcnt(0)
	v_pk_mul_f32 v[122:123], v[122:123], v[126:127]
	s_nop 0
	v_pk_fma_f32 v[86:87], v[118:119], v[122:123], v[86:87]
	v_pk_mul_f32 v[118:119], v[148:149], v[0:1] op_sel_hi:[1,0]
	v_pk_mul_f32 v[122:123], v[150:151], v[0:1] op_sel_hi:[1,0]
	v_pk_mul_f32 v[118:119], v[124:125], v[118:119]
	s_nop 0
	v_pk_fma_f32 v[88:89], v[120:121], v[118:119], v[88:89]
	ds_read_b128 v[118:121], v212 offset:3072
	global_store_dwordx4 v[164:165], v[86:89], off offset:2048
	s_waitcnt lgkmcnt(0)
; DI void rowpass(const Params& p, int l, bool first, int wv, char* smem) {
;     ...
; #pragma unroll
;       for (int i = 0; i < 8; ++i) {
;         const f32x4 gpv = *(const f32x4*)(lg_post + i * 256 + lane * 4);
; #pragma unroll
;         for (int e = 0; e < 4; ++e) hv[i][e] += gtv[i][e] * ((yv[i][e] * r1) * gpv[e]);
;         *(f32x4*)(hout + i * 256 + lane * 4) = hv[i];
;       }
;       if (l < 3) {
;         float s2 = 0.f;
; #pragma unroll
;         for (int i = 0; i < 8; ++i) s2 += hv[i][0] * hv[i][0] + hv[i][1] * hv[i][1] + hv[i][2] * hv[i][2] + hv[i][3] * hv[i][3];
;         s2 = wave_sum(s2);
;         const float r2 = rsqrtf(s2 * (1.f / DM) + EPSV);
;         u16* np = p.nbuf + (size_t)R * DM;
; #pragma unroll
;         for (int i = 0; i < 8; ++i) {
;           const f32x4 grv = *(const f32x4*)(lg_pre + i * 256 + lane * 4);
	v_pk_mul_f32 v[118:119], v[118:119], v[122:123]
	v_pk_fma_f32 v[82:83], v[114:115], v[118:119], v[82:83]
	v_pk_mul_f32 v[114:115], v[152:153], v[0:1] op_sel_hi:[1,0]
	v_pk_mul_f32 v[118:119], v[166:167], v[0:1] op_sel_hi:[1,0]
	v_pk_mul_f32 v[114:115], v[120:121], v[114:115]
	s_nop 0
	v_pk_fma_f32 v[84:85], v[116:117], v[114:115], v[84:85]
	ds_read_b128 v[114:117], v212 offset:4096
	global_store_dwordx4 v[164:165], v[82:85], off offset:3072
	s_waitcnt lgkmcnt(0)
	v_pk_mul_f32 v[114:115], v[114:115], v[118:119]
	v_pk_fma_f32 v[78:79], v[110:111], v[114:115], v[78:79]
	v_pk_mul_f32 v[110:111], v[168:169], v[0:1] op_sel_hi:[1,0]
	v_add_co_u32_e32 v114, vcc, s0, v164
	v_pk_mul_f32 v[110:111], v[116:117], v[110:111]
	v_pk_mul_f32 v[116:117], v[170:171], v[0:1] op_sel_hi:[1,0]
	v_pk_fma_f32 v[80:81], v[112:113], v[110:111], v[80:81]
	ds_read_b128 v[110:113], v212 offset:5120
	v_addc_co_u32_e32 v115, vcc, 0, v165, vcc
	s_and_b64 vcc, exec, s[4:5]
	global_store_dwordx4 v[114:115], v[78:81], off
	s_waitcnt lgkmcnt(0)
	v_pk_mul_f32 v[110:111], v[116:117], v[110:111]
	v_pk_fma_f32 v[74:75], v[106:107], v[110:111], v[74:75]
	v_pk_mul_f32 v[106:107], v[154:155], v[0:1] op_sel_hi:[1,0]
	v_pk_mul_f32 v[110:111], v[156:157], v[0:1] op_sel_hi:[1,0]
	v_pk_mul_f32 v[106:107], v[106:107], v[112:113]
	s_nop 0
	v_pk_fma_f32 v[76:77], v[108:109], v[106:107], v[76:77]
	ds_read_b128 v[106:109], v212 offset:6144
	global_store_dwordx4 v[114:115], v[74:77], off offset:1024
	s_waitcnt lgkmcnt(0)
	v_pk_mul_f32 v[106:107], v[110:111], v[106:107]
	v_pk_fma_f32 v[70:71], v[102:103], v[106:107], v[70:71]
	v_pk_mul_f32 v[102:103], v[158:159], v[0:1] op_sel_hi:[1,0]
	v_pk_mul_f32 v[106:107], v[160:161], v[0:1] op_sel_hi:[1,0]
	v_pk_mul_f32 v[102:103], v[102:103], v[108:109]
	s_nop 0
	v_pk_fma_f32 v[72:73], v[104:105], v[102:103], v[72:73]
	ds_read_b128 v[102:105], v212 offset:7168
	global_store_dwordx4 v[114:115], v[70:73], off offset:2048
	s_waitcnt lgkmcnt(0)
	v_pk_mul_f32 v[102:103], v[106:107], v[102:103]
	v_pk_fma_f32 v[66:67], v[98:99], v[102:103], v[66:67]
	v_pk_mul_f32 v[98:99], v[162:163], v[0:1] op_sel_hi:[1,0]
	s_nop 0
	v_pk_mul_f32 v[98:99], v[98:99], v[104:105]
	s_nop 0
	v_pk_fma_f32 v[68:69], v[100:101], v[98:99], v[68:69]
	global_store_dwordx4 v[114:115], v[66:69], off offset:3072
	s_cbranch_vccnz .LBB0_103
	v_mul_f32_e32 v0, v95, v95
	v_pk_fma_f32 v[98:99], v[94:95], v[94:95], v[0:1] op_sel_hi:[1,1,0]
	v_mul_f32_e32 v0, v97, v97
	v_pk_fma_f32 v[98:99], v[96:97], v[96:97], v[98:99]
	s_ashr_i32 s7, s6, 31
	v_pk_add_f32 v[98:99], v[0:1], v[98:99] op_sel_hi:[0,1]
	v_mul_f32_e32 v0, v91, v91
	v_pk_fma_f32 v[100:101], v[90:91], v[90:91], v[0:1] op_sel_hi:[1,1,0]
	v_mul_f32_e32 v0, v93, v93
	v_pk_fma_f32 v[100:101], v[92:93], v[92:93], v[100:101]
	s_lshl_b64 s[0:1], s[6:7], 12
	v_pk_add_f32 v[100:101], v[0:1], v[100:101] op_sel_hi:[0,1]
	v_mul_f32_e32 v0, v87, v87
	v_pk_add_f32 v[98:99], v[98:99], v[100:101]
	v_pk_fma_f32 v[100:101], v[86:87], v[86:87], v[0:1] op_sel_hi:[1,1,0]
	v_mul_f32_e32 v0, v89, v89
	v_pk_fma_f32 v[100:101], v[88:89], v[88:89], v[100:101]
	s_nop 0
	v_pk_add_f32 v[100:101], v[0:1], v[100:101] op_sel_hi:[0,1]
	v_mul_f32_e32 v0, v83, v83
	v_pk_add_f32 v[98:99], v[100:101], v[98:99]
	v_pk_fma_f32 v[100:101], v[82:83], v[82:83], v[0:1] op_sel_hi:[1,1,0]
	v_mul_f32_e32 v0, v85, v85
	v_pk_fma_f32 v[100:101], v[84:85], v[84:85], v[100:101]
	s_nop 0
	v_pk_add_f32 v[100:101], v[0:1], v[100:101] op_sel_hi:[0,1]
	v_mul_f32_e32 v0, v79, v79
	v_pk_add_f32 v[98:99], v[100:101], v[98:99]
	v_pk_fma_f32 v[100:101], v[78:79], v[78:79], v[0:1] op_sel_hi:[1,1,0]
	v_mul_f32_e32 v0, v81, v81
	v_pk_fma_f32 v[100:101], v[80:81], v[80:81], v[100:101]
	s_nop 0
	v_pk_add_f32 v[100:101], v[0:1], v[100:101] op_sel_hi:[0,1]
	v_mul_f32_e32 v0, v75, v75
	v_pk_add_f32 v[98:99], v[100:101], v[98:99]
	v_pk_fma_f32 v[100:101], v[74:75], v[74:75], v[0:1] op_sel_hi:[1,1,0]
	v_mul_f32_e32 v0, v77, v77
	v_pk_fma_f32 v[100:101], v[76:77], v[76:77], v[100:101]
	s_nop 0
	v_pk_add_f32 v[100:101], v[0:1], v[100:101] op_sel_hi:[0,1]
	v_mul_f32_e32 v0, v71, v71
	v_pk_add_f32 v[98:99], v[100:101], v[98:99]
	v_pk_fma_f32 v[100:101], v[70:71], v[70:71], v[0:1] op_sel_hi:[1,1,0]
	v_mul_f32_e32 v0, v73, v73
	v_pk_fma_f32 v[100:101], v[72:73], v[72:73], v[100:101]
	s_nop 0
	v_pk_add_f32 v[100:101], v[0:1], v[100:101] op_sel_hi:[0,1]
	v_mul_f32_e32 v0, v67, v67
	v_pk_add_f32 v[98:99], v[100:101], v[98:99]
	v_pk_fma_f32 v[100:101], v[66:67], v[66:67], v[0:1] op_sel_hi:[1,1,0]
	v_mul_f32_e32 v0, v69, v69
	v_pk_fma_f32 v[100:101], v[68:69], v[68:69], v[100:101]
	s_nop 0
	v_pk_add_f32 v[100:101], v[0:1], v[100:101] op_sel_hi:[0,1]
	v_pk_add_f32 v[98:99], v[100:101], v[98:99]
	ds_read_b128 v[100:103], v212 offset:8192
	v_mov_b32_e32 v0, v98
	s_nop 1
	v_permlane32_swap_b32_e32 v98, v0
	v_add_f32_e32 v0, v98, v0
	ds_swizzle_b32 v98, v0 offset:swizzle(SWAP,16)
	s_waitcnt lgkmcnt(0)
	v_add_f32_e32 v0, v0, v98
	ds_swizzle_b32 v98, v0 offset:swizzle(SWAP,8)
	s_waitcnt lgkmcnt(0)
	v_add_f32_e32 v0, v0, v98
	ds_swizzle_b32 v98, v0 offset:swizzle(SWAP,4)
	s_waitcnt lgkmcnt(0)
	v_add_f32_e32 v0, v0, v98
	ds_swizzle_b32 v98, v0 offset:swizzle(SWAP,2)
	s_waitcnt lgkmcnt(0)
; DI unsigned pack2(float a, float b) { f2_t v = {a, b}; bf2_t r = __builtin_convertvector(v, bf2_t); return __builtin_bit_cast(unsigned, r); }
; DI void rowpass(const Params& p, int l, bool first, int wv, char* smem) {
;     ...
;         s2 = wave_sum(s2);
;         const float r2 = rsqrtf(s2 * (1.f / DM) + EPSV);
;         u16* np = p.nbuf + (size_t)R * DM;
; #pragma unroll
;         for (int i = 0; i < 8; ++i) {
;           const f32x4 grv = *(const f32x4*)(lg_pre + i * 256 + lane * 4);
;           float o[4];
; #pragma unroll
;           for (int e = 0; e < 4; ++e) o[e] = ((hv[i][e] * r2) * grv[e]) * (1.f + scv[i][e]) + shv[i][e];
;           u32x2 pk; pk[0] = pack2(o[0], o[1]); pk[1] = pack2(o[2], o[3]);
;           *(u32x2*)(np + i * 256 + lane * 4) = pk;
;         }
	v_add_f32_e32 v0, v0, v98
	ds_swizzle_b32 v98, v0 offset:swizzle(SWAP,1)
	s_waitcnt lgkmcnt(0)
	v_add_f32_e32 v0, v0, v98
	v_fmamk_f32 v0, v0, 0x3a000000, v232
	v_cmp_gt_f32_e32 vcc, s2, v0
	v_mul_f32_e32 v98, 0x4b800000, v0
	s_nop 0
	v_cndmask_b32_e32 v0, v0, v98, vcc
	v_rsq_f32_e32 v0, v0
	s_nop 0
	v_mul_f32_e32 v98, 0x45800000, v0
	v_cndmask_b32_e32 v0, v0, v98, vcc
	v_pk_mul_f32 v[94:95], v[94:95], v[0:1] op_sel_hi:[1,0]
	v_pk_mul_f32 v[96:97], v[96:97], v[0:1] op_sel_hi:[1,0]
	v_pk_mul_f32 v[94:95], v[100:101], v[94:95]
	v_pk_add_f32 v[100:101], v[30:31], 1.0 op_sel_hi:[1,0]
	v_pk_mul_f32 v[96:97], v[102:103], v[96:97]
	v_pk_fma_f32 v[94:95], v[100:101], v[94:95], v[2:3]
	v_pk_add_f32 v[100:101], v[32:33], 1.0 op_sel_hi:[1,0]
	v_lshl_add_u64 v[98:99], v[134:135], 0, s[0:1]
	v_pk_fma_f32 v[96:97], v[100:101], v[96:97], v[4:5]
	v_cvt_pk_bf16_f32 v94, v94, v95
	v_cvt_pk_bf16_f32 v95, v96, v97
	global_store_dwordx2 v[98:99], v[94:95], off
	ds_read_b128 v[94:97], v212 offset:9216
	v_pk_mul_f32 v[90:91], v[90:91], v[0:1] op_sel_hi:[1,0]
	v_pk_mul_f32 v[92:93], v[92:93], v[0:1] op_sel_hi:[1,0]
	v_pk_mul_f32 v[86:87], v[86:87], v[0:1] op_sel_hi:[1,0]
	v_pk_mul_f32 v[88:89], v[88:89], v[0:1] op_sel_hi:[1,0]
	s_waitcnt lgkmcnt(0)
	v_pk_mul_f32 v[90:91], v[94:95], v[90:91]
	v_pk_add_f32 v[94:95], v[18:19], 1.0 op_sel_hi:[1,0]
	v_pk_mul_f32 v[92:93], v[96:97], v[92:93]
	v_pk_fma_f32 v[90:91], v[94:95], v[90:91], v[6:7]
	v_pk_add_f32 v[94:95], v[20:21], 1.0 op_sel_hi:[1,0]
	v_cvt_pk_bf16_f32 v90, v90, v91
	v_pk_fma_f32 v[92:93], v[94:95], v[92:93], v[8:9]
	v_pk_mul_f32 v[82:83], v[82:83], v[0:1] op_sel_hi:[1,0]
	v_cvt_pk_bf16_f32 v91, v92, v93
	global_store_dwordx2 v[98:99], v[90:91], off offset:512
	ds_read_b128 v[90:93], v212 offset:10240
	v_pk_mul_f32 v[84:85], v[84:85], v[0:1] op_sel_hi:[1,0]
	v_pk_mul_f32 v[78:79], v[78:79], v[0:1] op_sel_hi:[1,0]
	v_pk_mul_f32 v[80:81], v[80:81], v[0:1] op_sel_hi:[1,0]
	v_pk_mul_f32 v[74:75], v[74:75], v[0:1] op_sel_hi:[1,0]
	s_waitcnt lgkmcnt(0)
	v_pk_mul_f32 v[86:87], v[90:91], v[86:87]
	v_pk_add_f32 v[90:91], v[22:23], 1.0 op_sel_hi:[1,0]
	v_pk_mul_f32 v[88:89], v[92:93], v[88:89]
	v_pk_fma_f32 v[86:87], v[90:91], v[86:87], v[14:15]
	v_pk_add_f32 v[90:91], v[24:25], 1.0 op_sel_hi:[1,0]
	v_cvt_pk_bf16_f32 v86, v86, v87
	v_pk_fma_f32 v[88:89], v[90:91], v[88:89], v[16:17]
	v_pk_mul_f32 v[76:77], v[76:77], v[0:1] op_sel_hi:[1,0]
	v_cvt_pk_bf16_f32 v87, v88, v89
	global_store_dwordx2 v[98:99], v[86:87], off offset:1024
	ds_read_b128 v[86:89], v212 offset:11264
	v_pk_mul_f32 v[70:71], v[70:71], v[0:1] op_sel_hi:[1,0]
	v_pk_mul_f32 v[72:73], v[72:73], v[0:1] op_sel_hi:[1,0]
	v_pk_mul_f32 v[66:67], v[66:67], v[0:1] op_sel_hi:[1,0]
	v_pk_mul_f32 v[68:69], v[68:69], v[0:1] op_sel_hi:[1,0]
	s_waitcnt lgkmcnt(0)
	v_pk_mul_f32 v[82:83], v[86:87], v[82:83]
	v_pk_add_f32 v[86:87], v[26:27], 1.0 op_sel_hi:[1,0]
	v_pk_mul_f32 v[84:85], v[88:89], v[84:85]
	v_pk_fma_f32 v[82:83], v[86:87], v[82:83], v[10:11]
	v_pk_add_f32 v[86:87], v[28:29], 1.0 op_sel_hi:[1,0]
	v_cvt_pk_bf16_f32 v82, v82, v83
	v_pk_fma_f32 v[84:85], v[86:87], v[84:85], v[12:13]
	s_nop 0
	v_cvt_pk_bf16_f32 v83, v84, v85
	global_store_dwordx2 v[98:99], v[82:83], off offset:1536
	ds_read_b128 v[82:85], v212 offset:12288
	s_waitcnt lgkmcnt(0)
	v_pk_mul_f32 v[78:79], v[82:83], v[78:79]
	v_pk_add_f32 v[82:83], v[54:55], 1.0 op_sel_hi:[1,0]
	v_pk_mul_f32 v[80:81], v[84:85], v[80:81]
	v_pk_fma_f32 v[78:79], v[82:83], v[78:79], v[34:35]
	v_pk_add_f32 v[82:83], v[56:57], 1.0 op_sel_hi:[1,0]
	v_cvt_pk_bf16_f32 v78, v78, v79
	v_pk_fma_f32 v[80:81], v[82:83], v[80:81], v[36:37]
	s_nop 0
	v_cvt_pk_bf16_f32 v79, v80, v81
	global_store_dwordx2 v[98:99], v[78:79], off offset:2048
	ds_read_b128 v[78:81], v212 offset:13312
	s_waitcnt lgkmcnt(0)
	v_pk_mul_f32 v[74:75], v[74:75], v[78:79]
	v_pk_add_f32 v[78:79], v[50:51], 1.0 op_sel_hi:[1,0]
	v_pk_mul_f32 v[76:77], v[76:77], v[80:81]
	v_pk_fma_f32 v[74:75], v[78:79], v[74:75], v[38:39]
	v_pk_add_f32 v[78:79], v[52:53], 1.0 op_sel_hi:[1,0]
	v_cvt_pk_bf16_f32 v74, v74, v75
	v_pk_fma_f32 v[76:77], v[78:79], v[76:77], v[40:41]
	s_nop 0
	v_cvt_pk_bf16_f32 v75, v76, v77
	global_store_dwordx2 v[98:99], v[74:75], off offset:2560
	ds_read_b128 v[74:77], v212 offset:14336
	s_waitcnt lgkmcnt(0)
	v_pk_mul_f32 v[70:71], v[70:71], v[74:75]
	v_pk_add_f32 v[74:75], v[62:63], 1.0 op_sel_hi:[1,0]
	v_pk_mul_f32 v[72:73], v[72:73], v[76:77]
	v_pk_fma_f32 v[70:71], v[74:75], v[70:71], v[42:43]
	v_pk_add_f32 v[74:75], v[64:65], 1.0 op_sel_hi:[1,0]
	v_cvt_pk_bf16_f32 v70, v70, v71
	v_pk_fma_f32 v[72:73], v[74:75], v[72:73], v[44:45]
	s_nop 0
	v_cvt_pk_bf16_f32 v71, v72, v73
	global_store_dwordx2 v[98:99], v[70:71], off offset:3072
	ds_read_b128 v[70:73], v212 offset:15360
	s_waitcnt lgkmcnt(0)
	v_pk_mul_f32 v[66:67], v[66:67], v[70:71]
	v_pk_add_f32 v[70:71], v[58:59], 1.0 op_sel_hi:[1,0]
	v_pk_mul_f32 v[68:69], v[68:69], v[72:73]
	v_pk_fma_f32 v[66:67], v[70:71], v[66:67], v[46:47]
	v_pk_add_f32 v[70:71], v[60:61], 1.0 op_sel_hi:[1,0]
	v_cvt_pk_bf16_f32 v66, v66, v67
	v_pk_fma_f32 v[68:69], v[70:71], v[68:69], v[48:49]
	s_nop 0
	v_cvt_pk_bf16_f32 v67, v68, v69
	global_store_dwordx2 v[98:99], v[66:67], off offset:3584
	s_branch .LBB0_103
